# scan step tops 6..19: counted wait leaves the previous step's two park stores in flight (partner reads them at step 38-p >= p+3)
# baseline (speedup 1.0000x reference)
; __device__ __forceinline__ bool scan_needfin(int s) { return s >= 0 && s < 35 && !scan_first(s + 1) && s + 1 != 20 && s + 1 != 2; }
;     ...
;     if (s == 21 || s == 3) asm volatile("s_waitcnt vmcnt(0)" ::: "memory");
;     else if (scan_needfin(s - 1)) { if (GDN) asm volatile("s_waitcnt vmcnt(14)" ::: "memory"); else asm volatile("s_waitcnt vmcnt(15)" ::: "memory"); }
;     else { if (GDN) asm volatile("s_waitcnt vmcnt(8)" ::: "memory"); else asm volatile("s_waitcnt vmcnt(9)" ::: "memory"); }
;     __syncthreads();
.LBB0_366:
	s_add_i32 s98, s25, -6
	s_cmp_lt_u32 s98, 14
	s_cbranch_scc1 .Lh2_m0
	s_waitcnt vmcnt(9)
	s_branch .Lh2d_m0
.Lh2_m0:
	s_waitcnt vmcnt(11)
.Lh2d_m0:
	s_cbranch_execz .LBB0_351
	s_branch .LBB0_352
.LBB0_367:
	s_mov_b64 s[12:13], 0
	s_mov_b64 s[14:15], 0

; __device__ __forceinline__ bool scan_needfin(int s) { return s >= 0 && s < 35 && !scan_first(s + 1) && s + 1 != 20 && s + 1 != 2; }
;     ...
;     if (s == 21 || s == 3) asm volatile("s_waitcnt vmcnt(0)" ::: "memory");
;     else if (scan_needfin(s - 1)) { if (GDN) asm volatile("s_waitcnt vmcnt(14)" ::: "memory"); else asm volatile("s_waitcnt vmcnt(15)" ::: "memory"); }
;     else { if (GDN) asm volatile("s_waitcnt vmcnt(8)" ::: "memory"); else asm volatile("s_waitcnt vmcnt(9)" ::: "memory"); }
;     __syncthreads();
.LBB0_369:
	s_andn2_b64 vcc, exec, s[14:15]
	s_cbranch_vccnz .LBB0_375
	s_cmp_lt_u32 s25, 35
	s_cselect_b64 s[6:7], -1, 0
	s_cmp_gt_u32 s25, 2
	s_cselect_b32 s1, 20, 2
	s_cmp_ge_u32 s4, s1
	s_cselect_b64 s[8:9], -1, 0
	s_and_b64 s[6:7], s[6:7], s[8:9]
	s_andn2_b64 vcc, exec, s[6:7]
	s_mov_b64 s[12:13], -1
	s_cbranch_vccz .LBB0_372
	s_add_i32 s98, s25, -5
	s_cmp_lt_u32 s98, 14
	s_cbranch_scc1 .Lh2_m1
	s_waitcnt vmcnt(9)
	s_branch .Lh2d_m1
.Lh2_m1:
	s_waitcnt vmcnt(11)
.Lh2d_m1:
	s_mov_b64 s[12:13], 0
.LBB0_372:
	s_andn2_b64 vcc, exec, s[12:13]
	s_cbranch_vccnz .LBB0_374
	s_waitcnt vmcnt(19)

; __device__ __forceinline__ bool scan_needfin(int s) { return s >= 0 && s < 35 && !scan_first(s + 1) && s + 1 != 20 && s + 1 != 2; }
;     ...
;     if (s == 21 || s == 3) asm volatile("s_waitcnt vmcnt(0)" ::: "memory");
;     else if (scan_needfin(s - 1)) { if (GDN) asm volatile("s_waitcnt vmcnt(14)" ::: "memory"); else asm volatile("s_waitcnt vmcnt(15)" ::: "memory"); }
;     else { if (GDN) asm volatile("s_waitcnt vmcnt(8)" ::: "memory"); else asm volatile("s_waitcnt vmcnt(9)" ::: "memory"); }
;     __syncthreads();
.LBB0_398:
	s_cmp_gt_u32 s25, 18
	s_cselect_b64 s[6:7], -1, 0
	s_and_b64 s[6:7], s[18:19], s[6:7]
	s_andn2_b64 vcc, exec, s[6:7]
	s_mov_b64 s[10:11], -1
	s_cbranch_vccz .LBB0_400
	s_add_i32 s98, s25, -4
	s_cmp_lt_u32 s98, 14
	s_cbranch_scc1 .Lh2_m2
	s_waitcnt vmcnt(9)
	s_branch .Lh2d_m2
.Lh2_m2:
	s_waitcnt vmcnt(11)
.Lh2d_m2:
	s_mov_b64 s[10:11], 0
.LBB0_400:
	s_andn2_b64 vcc, exec, s[10:11]
	s_cbranch_vccnz .LBB0_402
	s_waitcnt vmcnt(19)

; __device__ __forceinline__ bool scan_needfin(int s) { return s >= 0 && s < 35 && !scan_first(s + 1) && s + 1 != 20 && s + 1 != 2; }
;     ...
;     if (s == 21 || s == 3) asm volatile("s_waitcnt vmcnt(0)" ::: "memory");
;     else if (scan_needfin(s - 1)) { if (GDN) asm volatile("s_waitcnt vmcnt(14)" ::: "memory"); else asm volatile("s_waitcnt vmcnt(15)" ::: "memory"); }
;     else { if (GDN) asm volatile("s_waitcnt vmcnt(8)" ::: "memory"); else asm volatile("s_waitcnt vmcnt(9)" ::: "memory"); }
;     __syncthreads();
.LBB0_419:
	s_andn2_b64 vcc, exec, s[12:13]
	s_cbranch_vccnz .LBB0_425
	s_sub_i32 s4, s25, 17
	s_cmp_gt_u32 s4, 15
	s_mov_b64 s[10:11], -1
	s_cbranch_scc0 .LBB0_422
	s_add_i32 s98, s25, -3
	s_cmp_lt_u32 s98, 14
	s_cbranch_scc1 .Lh2_m3
	s_waitcnt vmcnt(9)
	s_branch .Lh2d_m3
.Lh2_m3:
	s_waitcnt vmcnt(11)
.Lh2d_m3:
	s_mov_b64 s[10:11], 0
.LBB0_422:
	s_andn2_b64 vcc, exec, s[10:11]
	s_cbranch_vccnz .LBB0_424
	s_waitcnt vmcnt(19)

; __device__ __forceinline__ bool scan_needfin(int s) { return s >= 0 && s < 35 && !scan_first(s + 1) && s + 1 != 20 && s + 1 != 2; }
;     ...
;     if (s == 21 || s == 3) asm volatile("s_waitcnt vmcnt(0)" ::: "memory");
;     else if (scan_needfin(s - 1)) { if (GDN) asm volatile("s_waitcnt vmcnt(14)" ::: "memory"); else asm volatile("s_waitcnt vmcnt(15)" ::: "memory"); }
;     else { if (GDN) asm volatile("s_waitcnt vmcnt(8)" ::: "memory"); else asm volatile("s_waitcnt vmcnt(9)" ::: "memory"); }
;     __syncthreads();
.LBB0_452:
	s_add_i32 s98, s25, -2
	s_cmp_lt_u32 s98, 14
	s_cbranch_scc1 .Lh2_m4
	s_waitcnt vmcnt(9)
	s_branch .Lh2d_m4
.Lh2_m4:
	s_waitcnt vmcnt(11)
.Lh2d_m4:
	s_cbranch_execz .LBB0_440
	s_branch .LBB0_441

; __device__ __forceinline__ bool scan_needfin(int s) { return s >= 0 && s < 35 && !scan_first(s + 1) && s + 1 != 20 && s + 1 != 2; }
;     ...
;     if (s == 21 || s == 3) asm volatile("s_waitcnt vmcnt(0)" ::: "memory");
;     else if (scan_needfin(s - 1)) { if (GDN) asm volatile("s_waitcnt vmcnt(14)" ::: "memory"); else asm volatile("s_waitcnt vmcnt(15)" ::: "memory"); }
;     else { if (GDN) asm volatile("s_waitcnt vmcnt(8)" ::: "memory"); else asm volatile("s_waitcnt vmcnt(9)" ::: "memory"); }
;     __syncthreads();
.LBB0_458:
	s_cmp_lg_u32 s25, 16
	s_cselect_b64 s[10:11], -1, 0
	s_mov_b64 s[12:13], -1
	s_and_b64 vcc, exec, s[10:11]
	s_cbranch_vccz .LBB0_464
	s_add_i32 s0, s25, -15
	s_cmp_gt_u32 s0, 15
	s_cbranch_scc0 .LBB0_461
	s_add_i32 s98, s25, -1
	s_cmp_lt_u32 s98, 14
	s_cbranch_scc1 .Lh2_m5
	s_waitcnt vmcnt(9)
	s_branch .Lh2d_m5
.Lh2_m5:
	s_waitcnt vmcnt(11)
.Lh2d_m5:
	s_mov_b64 s[12:13], 0
.LBB0_461:
	s_andn2_b64 vcc, exec, s[12:13]
	s_cbranch_vccnz .LBB0_463
	s_waitcnt vmcnt(19)

; __device__ __forceinline__ bool scan_needfin(int s) { return s >= 0 && s < 35 && !scan_first(s + 1) && s + 1 != 20 && s + 1 != 2; }
;     ...
;     if (s == 21 || s == 3) asm volatile("s_waitcnt vmcnt(0)" ::: "memory");
;     else if (scan_needfin(s - 1)) { if (GDN) asm volatile("s_waitcnt vmcnt(14)" ::: "memory"); else asm volatile("s_waitcnt vmcnt(15)" ::: "memory"); }
;     else { if (GDN) asm volatile("s_waitcnt vmcnt(8)" ::: "memory"); else asm volatile("s_waitcnt vmcnt(9)" ::: "memory"); }
;     __syncthreads();
.LBB0_501:
	s_add_i32 s98, s23, -6
	s_cmp_lt_u32 s98, 14
	s_cbranch_scc1 .Lh2_g0
	s_waitcnt vmcnt(8)
	s_branch .Lh2d_g0
.Lh2_g0:
	s_waitcnt vmcnt(10)
.Lh2d_g0:
	s_cbranch_execz .LBB0_486
	s_branch .LBB0_487
.LBB0_502:
	s_mov_b64 s[12:13], 0
	s_mov_b64 s[14:15], 0

; __device__ __forceinline__ bool scan_needfin(int s) { return s >= 0 && s < 35 && !scan_first(s + 1) && s + 1 != 20 && s + 1 != 2; }
;     ...
;     if (s == 21 || s == 3) asm volatile("s_waitcnt vmcnt(0)" ::: "memory");
;     else if (scan_needfin(s - 1)) { if (GDN) asm volatile("s_waitcnt vmcnt(14)" ::: "memory"); else asm volatile("s_waitcnt vmcnt(15)" ::: "memory"); }
;     else { if (GDN) asm volatile("s_waitcnt vmcnt(8)" ::: "memory"); else asm volatile("s_waitcnt vmcnt(9)" ::: "memory"); }
;     __syncthreads();
.LBB0_504:
	s_andn2_b64 vcc, exec, s[14:15]
	s_cbranch_vccnz .LBB0_510
	s_cmp_lt_u32 s23, 35
	s_cselect_b64 s[6:7], -1, 0
	s_cmp_gt_u32 s23, 2
	s_cselect_b32 s1, 20, 2
	s_cmp_ge_u32 s4, s1
	s_cselect_b64 s[8:9], -1, 0
	s_and_b64 s[6:7], s[6:7], s[8:9]
	s_andn2_b64 vcc, exec, s[6:7]
	s_mov_b64 s[12:13], -1
	s_cbranch_vccz .LBB0_507
	s_add_i32 s98, s23, -5
	s_cmp_lt_u32 s98, 14
	s_cbranch_scc1 .Lh2_g1
	s_waitcnt vmcnt(8)
	s_branch .Lh2d_g1

; __device__ __forceinline__ bool scan_needfin(int s) { return s >= 0 && s < 35 && !scan_first(s + 1) && s + 1 != 20 && s + 1 != 2; }
;     ...
;     if (s == 21 || s == 3) asm volatile("s_waitcnt vmcnt(0)" ::: "memory");
;     else if (scan_needfin(s - 1)) { if (GDN) asm volatile("s_waitcnt vmcnt(14)" ::: "memory"); else asm volatile("s_waitcnt vmcnt(15)" ::: "memory"); }
;     else { if (GDN) asm volatile("s_waitcnt vmcnt(8)" ::: "memory"); else asm volatile("s_waitcnt vmcnt(9)" ::: "memory"); }
;     __syncthreads();
.Lh2d_g1:
	s_mov_b64 s[12:13], 0
.LBB0_507:
	s_andn2_b64 vcc, exec, s[12:13]
	s_cbranch_vccnz .LBB0_509
	s_waitcnt vmcnt(18)

; __device__ __forceinline__ bool scan_needfin(int s) { return s >= 0 && s < 35 && !scan_first(s + 1) && s + 1 != 20 && s + 1 != 2; }
;     ...
;     if (s == 21 || s == 3) asm volatile("s_waitcnt vmcnt(0)" ::: "memory");
;     else if (scan_needfin(s - 1)) { if (GDN) asm volatile("s_waitcnt vmcnt(14)" ::: "memory"); else asm volatile("s_waitcnt vmcnt(15)" ::: "memory"); }
;     else { if (GDN) asm volatile("s_waitcnt vmcnt(8)" ::: "memory"); else asm volatile("s_waitcnt vmcnt(9)" ::: "memory"); }
;     __syncthreads();
.LBB0_533:
	s_cmp_gt_u32 s23, 18
	s_cselect_b64 s[6:7], -1, 0
	s_and_b64 s[6:7], s[18:19], s[6:7]
	s_andn2_b64 vcc, exec, s[6:7]
	s_mov_b64 s[10:11], -1
	s_cbranch_vccz .LBB0_535
	s_add_i32 s98, s23, -4
	s_cmp_lt_u32 s98, 14
	s_cbranch_scc1 .Lh2_g2
	s_waitcnt vmcnt(8)
	s_branch .Lh2d_g2

; __device__ __forceinline__ bool scan_needfin(int s) { return s >= 0 && s < 35 && !scan_first(s + 1) && s + 1 != 20 && s + 1 != 2; }
;     ...
;     if (s == 21 || s == 3) asm volatile("s_waitcnt vmcnt(0)" ::: "memory");
;     else if (scan_needfin(s - 1)) { if (GDN) asm volatile("s_waitcnt vmcnt(14)" ::: "memory"); else asm volatile("s_waitcnt vmcnt(15)" ::: "memory"); }
;     else { if (GDN) asm volatile("s_waitcnt vmcnt(8)" ::: "memory"); else asm volatile("s_waitcnt vmcnt(9)" ::: "memory"); }
;     __syncthreads();
.Lh2d_g2:
	s_mov_b64 s[10:11], 0
.LBB0_535:
	s_andn2_b64 vcc, exec, s[10:11]
	s_cbranch_vccnz .LBB0_537
	s_waitcnt vmcnt(18)

; __device__ __forceinline__ bool scan_needfin(int s) { return s >= 0 && s < 35 && !scan_first(s + 1) && s + 1 != 20 && s + 1 != 2; }
;     ...
;     if (s == 21 || s == 3) asm volatile("s_waitcnt vmcnt(0)" ::: "memory");
;     else if (scan_needfin(s - 1)) { if (GDN) asm volatile("s_waitcnt vmcnt(14)" ::: "memory"); else asm volatile("s_waitcnt vmcnt(15)" ::: "memory"); }
;     else { if (GDN) asm volatile("s_waitcnt vmcnt(8)" ::: "memory"); else asm volatile("s_waitcnt vmcnt(9)" ::: "memory"); }
;     __syncthreads();
.LBB0_553:
	s_andn2_b64 vcc, exec, s[12:13]
	s_cbranch_vccnz .LBB0_559
	s_sub_i32 s4, s23, 17
	s_cmp_gt_u32 s4, 15
	s_mov_b64 s[10:11], -1
	s_cbranch_scc0 .LBB0_556
	s_add_i32 s98, s23, -3
	s_cmp_lt_u32 s98, 14
	s_cbranch_scc1 .Lh2_g3
	s_waitcnt vmcnt(8)
	s_branch .Lh2d_g3

; __device__ __forceinline__ bool scan_needfin(int s) { return s >= 0 && s < 35 && !scan_first(s + 1) && s + 1 != 20 && s + 1 != 2; }
;     ...
;     if (s == 21 || s == 3) asm volatile("s_waitcnt vmcnt(0)" ::: "memory");
;     else if (scan_needfin(s - 1)) { if (GDN) asm volatile("s_waitcnt vmcnt(14)" ::: "memory"); else asm volatile("s_waitcnt vmcnt(15)" ::: "memory"); }
;     else { if (GDN) asm volatile("s_waitcnt vmcnt(8)" ::: "memory"); else asm volatile("s_waitcnt vmcnt(9)" ::: "memory"); }
;     __syncthreads();
.Lh2d_g3:
	s_mov_b64 s[10:11], 0
.LBB0_556:
	s_andn2_b64 vcc, exec, s[10:11]
	s_cbranch_vccnz .LBB0_558
	s_waitcnt vmcnt(18)

; __device__ __forceinline__ bool scan_needfin(int s) { return s >= 0 && s < 35 && !scan_first(s + 1) && s + 1 != 20 && s + 1 != 2; }
;     ...
;     if (s == 21 || s == 3) asm volatile("s_waitcnt vmcnt(0)" ::: "memory");
;     else if (scan_needfin(s - 1)) { if (GDN) asm volatile("s_waitcnt vmcnt(14)" ::: "memory"); else asm volatile("s_waitcnt vmcnt(15)" ::: "memory"); }
;     else { if (GDN) asm volatile("s_waitcnt vmcnt(8)" ::: "memory"); else asm volatile("s_waitcnt vmcnt(9)" ::: "memory"); }
;     __syncthreads();
.LBB0_583:
	s_add_i32 s98, s23, -2
	s_cmp_lt_u32 s98, 14
	s_cbranch_scc1 .Lh2_g4
	s_waitcnt vmcnt(8)
	s_branch .Lh2d_g4

; __device__ __forceinline__ bool scan_needfin(int s) { return s >= 0 && s < 35 && !scan_first(s + 1) && s + 1 != 20 && s + 1 != 2; }
;     ...
;     if (s == 21 || s == 3) asm volatile("s_waitcnt vmcnt(0)" ::: "memory");
;     else if (scan_needfin(s - 1)) { if (GDN) asm volatile("s_waitcnt vmcnt(14)" ::: "memory"); else asm volatile("s_waitcnt vmcnt(15)" ::: "memory"); }
;     else { if (GDN) asm volatile("s_waitcnt vmcnt(8)" ::: "memory"); else asm volatile("s_waitcnt vmcnt(9)" ::: "memory"); }
;     __syncthreads();
.LBB0_591:
	s_cmp_lg_u32 s23, 16
	s_cselect_b64 s[10:11], -1, 0
	s_mov_b64 s[12:13], -1
	s_and_b64 vcc, exec, s[10:11]
	s_cbranch_vccz .LBB0_597
	s_add_i32 s0, s23, -15
	s_cmp_gt_u32 s0, 15
	s_cbranch_scc0 .LBB0_594
	s_add_i32 s98, s23, -1
	s_cmp_lt_u32 s98, 14
	s_cbranch_scc1 .Lh2_g5
	s_waitcnt vmcnt(8)
	s_branch .Lh2d_g5

; __device__ __forceinline__ bool scan_needfin(int s) { return s >= 0 && s < 35 && !scan_first(s + 1) && s + 1 != 20 && s + 1 != 2; }
;     ...
;     if (s == 21 || s == 3) asm volatile("s_waitcnt vmcnt(0)" ::: "memory");
;     else if (scan_needfin(s - 1)) { if (GDN) asm volatile("s_waitcnt vmcnt(14)" ::: "memory"); else asm volatile("s_waitcnt vmcnt(15)" ::: "memory"); }
;     else { if (GDN) asm volatile("s_waitcnt vmcnt(8)" ::: "memory"); else asm volatile("s_waitcnt vmcnt(9)" ::: "memory"); }
;     __syncthreads();
.Lh2d_g5:
	s_mov_b64 s[12:13], 0
.LBB0_594:
	s_andn2_b64 vcc, exec, s[12:13]
	s_cbranch_vccnz .LBB0_596
	s_waitcnt vmcnt(18)
